# attn: next item's Q fragments prefetched at the epilogue start (before the output stores) so the item prologue waits vmcnt(16) instead of draining stores and a fresh Q load
# baseline (speedup 1.0000x reference)
.LBB0_248:
	s_mov_b32 s86, 0x5046000
	s_mov_b32 s87, 0
	v_lshl_add_u64 v[156:157], v[178:179], 0, s[86:87]
	global_load_dwordx4 v[108:111], v[156:157], off
	global_load_dwordx4 v[100:103], v[156:157], off offset:64
	global_load_dwordx4 v[104:107], v[156:157], off offset:128
	global_load_dwordx4 v[112:115], v[156:157], off offset:192
	ds_bpermute_b32 v0, v159, v222
	s_lshl_b32 s0, s14, 14
	s_add_u32 s0, s0, s15
	s_addc_u32 s8, 0, s16
	s_ashr_i32 s9, s18, 31
	s_waitcnt lgkmcnt(0)
	v_add_f32_e32 v2, v222, v0
	ds_bpermute_b32 v3, v160, v2
	s_add_u32 s0, s0, s18
	s_addc_u32 s8, s8, s9
	v_or_b32_e32 v0, s0, v165
	v_mov_b32_e32 v1, s8
	s_waitcnt lgkmcnt(0)
	v_add_f32_e32 v2, v2, v3
	v_rcp_f32_e32 v4, v2
	v_lshlrev_b64 v[0:1], 12, v[0:1]
	v_lshl_add_u64 v[0:1], s[6:7], 0, v[0:1]
	s_lshl_b32 s0, s13, 1
	v_lshl_add_u64 v[0:1], v[0:1], 0, s[0:1]
	v_mov_b32_e32 v64, v158
	v_lshl_add_u64 v[6:7], v[0:1], 0, v[64:65]
	v_pk_mul_f32 v[0:1], v[96:97], v[4:5] op_sel_hi:[1,0]
	v_pk_mul_f32 v[2:3], v[98:99], v[4:5] op_sel_hi:[1,0]
	v_cvt_pk_bf16_f32 v0, v0, v1
	v_cvt_pk_bf16_f32 v1, v2, v3
	global_store_dwordx2 v[6:7], v[0:1], off offset:0 nt
	s_add_i32 s12, s12, s42
	s_add_i32 s10, s10, s11
	v_pk_mul_f32 v[8:9], v[88:89], v[4:5] op_sel_hi:[1,0]
	v_pk_mul_f32 v[10:11], v[90:91], v[4:5] op_sel_hi:[1,0]
	v_cvt_pk_bf16_f32 v8, v8, v9
	v_cvt_pk_bf16_f32 v9, v10, v11
	global_store_dwordx2 v[6:7], v[8:9], off offset:32 nt
	v_pk_mul_f32 v[0:1], v[80:81], v[4:5] op_sel_hi:[1,0]
	v_pk_mul_f32 v[2:3], v[82:83], v[4:5] op_sel_hi:[1,0]
	v_cvt_pk_bf16_f32 v0, v0, v1
	v_cvt_pk_bf16_f32 v1, v2, v3
	global_store_dwordx2 v[6:7], v[0:1], off offset:64 nt
	v_pk_mul_f32 v[8:9], v[72:73], v[4:5] op_sel_hi:[1,0]
	v_pk_mul_f32 v[10:11], v[74:75], v[4:5] op_sel_hi:[1,0]
	v_cvt_pk_bf16_f32 v8, v8, v9
	v_cvt_pk_bf16_f32 v9, v10, v11
	global_store_dwordx2 v[6:7], v[8:9], off offset:96 nt
	v_pk_mul_f32 v[0:1], v[56:57], v[4:5] op_sel_hi:[1,0]
	v_pk_mul_f32 v[2:3], v[58:59], v[4:5] op_sel_hi:[1,0]
	v_cvt_pk_bf16_f32 v0, v0, v1
	v_cvt_pk_bf16_f32 v1, v2, v3
	global_store_dwordx2 v[6:7], v[0:1], off offset:128 nt
	v_pk_mul_f32 v[8:9], v[48:49], v[4:5] op_sel_hi:[1,0]
	v_pk_mul_f32 v[10:11], v[50:51], v[4:5] op_sel_hi:[1,0]
	v_cvt_pk_bf16_f32 v8, v8, v9
	v_cvt_pk_bf16_f32 v9, v10, v11
	global_store_dwordx2 v[6:7], v[8:9], off offset:160 nt
	v_pk_mul_f32 v[0:1], v[40:41], v[4:5] op_sel_hi:[1,0]
	v_pk_mul_f32 v[2:3], v[42:43], v[4:5] op_sel_hi:[1,0]
	v_cvt_pk_bf16_f32 v0, v0, v1
	v_cvt_pk_bf16_f32 v1, v2, v3
	global_store_dwordx2 v[6:7], v[0:1], off offset:192 nt
	v_pk_mul_f32 v[8:9], v[32:33], v[4:5] op_sel_hi:[1,0]
	v_pk_mul_f32 v[10:11], v[34:35], v[4:5] op_sel_hi:[1,0]
	v_cvt_pk_bf16_f32 v8, v8, v9
	v_cvt_pk_bf16_f32 v9, v10, v11
	global_store_dwordx2 v[6:7], v[8:9], off offset:224 nt
	v_pk_mul_f32 v[0:1], v[92:93], v[4:5] op_sel_hi:[1,0]
	v_pk_mul_f32 v[2:3], v[94:95], v[4:5] op_sel_hi:[1,0]
	v_cvt_pk_bf16_f32 v0, v0, v1
	v_cvt_pk_bf16_f32 v1, v2, v3
	global_store_dwordx2 v[6:7], v[0:1], off offset:256 nt
	v_pk_mul_f32 v[8:9], v[84:85], v[4:5] op_sel_hi:[1,0]
	v_pk_mul_f32 v[10:11], v[86:87], v[4:5] op_sel_hi:[1,0]
	v_cvt_pk_bf16_f32 v8, v8, v9
	v_cvt_pk_bf16_f32 v9, v10, v11
	global_store_dwordx2 v[6:7], v[8:9], off offset:288 nt
	v_pk_mul_f32 v[0:1], v[76:77], v[4:5] op_sel_hi:[1,0]
	v_pk_mul_f32 v[2:3], v[78:79], v[4:5] op_sel_hi:[1,0]
	v_cvt_pk_bf16_f32 v0, v0, v1
	v_cvt_pk_bf16_f32 v1, v2, v3
	global_store_dwordx2 v[6:7], v[0:1], off offset:320 nt
	v_pk_mul_f32 v[8:9], v[68:69], v[4:5] op_sel_hi:[1,0]
	v_pk_mul_f32 v[10:11], v[70:71], v[4:5] op_sel_hi:[1,0]
	v_cvt_pk_bf16_f32 v8, v8, v9
	v_cvt_pk_bf16_f32 v9, v10, v11
	global_store_dwordx2 v[6:7], v[8:9], off offset:352 nt
	v_pk_mul_f32 v[0:1], v[60:61], v[4:5] op_sel_hi:[1,0]
	v_pk_mul_f32 v[2:3], v[62:63], v[4:5] op_sel_hi:[1,0]
	v_cvt_pk_bf16_f32 v0, v0, v1
	v_cvt_pk_bf16_f32 v1, v2, v3
	global_store_dwordx2 v[6:7], v[0:1], off offset:384 nt
	v_pk_mul_f32 v[8:9], v[52:53], v[4:5] op_sel_hi:[1,0]
	v_pk_mul_f32 v[10:11], v[54:55], v[4:5] op_sel_hi:[1,0]
	v_cvt_pk_bf16_f32 v8, v8, v9
	v_cvt_pk_bf16_f32 v9, v10, v11
	global_store_dwordx2 v[6:7], v[8:9], off offset:416 nt
	v_pk_mul_f32 v[0:1], v[44:45], v[4:5] op_sel_hi:[1,0]
	v_pk_mul_f32 v[2:3], v[46:47], v[4:5] op_sel_hi:[1,0]
	v_cvt_pk_bf16_f32 v0, v0, v1
	v_cvt_pk_bf16_f32 v1, v2, v3
	global_store_dwordx2 v[6:7], v[0:1], off offset:448 nt
	v_pk_mul_f32 v[8:9], v[36:37], v[4:5] op_sel_hi:[1,0]
	v_pk_mul_f32 v[10:11], v[38:39], v[4:5] op_sel_hi:[1,0]
	v_cvt_pk_bf16_f32 v8, v8, v9
	v_cvt_pk_bf16_f32 v9, v10, v11
	global_store_dwordx2 v[6:7], v[8:9], off offset:480 nt
	s_cmpk_gt_i32 s12, 0x7ff
	s_nop 0
	s_cbranch_scc1 .LBB0_262
.LBB0_249:
	s_nop 0
	v_mov_b32_e32 v0, v65
	s_bfe_u32 s19, s12, 0x30005
	s_waitcnt vmcnt(19)
	v_add_u32_e32 v116, v0, v190
	v_cmp_gt_i32_e32 vcc, s28, v116
	s_barrier
	s_cmp_lg_u32 s32, 0
	s_cbranch_scc0 .Lch_full0
	s_mov_b64 s[8:9], exec
	s_branch .LBB0_251
.Lch_full0:
	s_and_saveexec_b64 s[8:9], vcc
	s_cbranch_execz .LBB0_251
	s_movk_i32 s0, 0x80
	v_add_u32_e32 v0, 0xffffff80, v116
	v_sub_u32_e32 v1, 0x80, v116
	v_cmp_gt_i32_e32 vcc, s0, v116
	s_mov_b32 s13, 0x40317218
	v_readlane_b32 s52, v252, 25
	v_cndmask_b32_e32 v0, v0, v1, vcc
	v_max_i32_e32 v1, 1, v0
	v_cvt_f32_u32_e32 v1, v1
	v_readlane_b32 s60, v252, 33
	v_readlane_b32 s61, v252, 34
	v_readlane_b32 s53, v252, 26
	v_mul_f32_e32 v1, 0x3e000000, v1
	v_cmp_gt_f32_e32 vcc, s92, v1
	v_readlane_b32 s54, v252, 27
	v_readlane_b32 s55, v252, 28
	v_cndmask_b32_e64 v2, 0, 32, vcc
	v_ldexp_f32 v1, v1, v2
	v_log_f32_e32 v1, v1
	v_cndmask_b32_e32 v2, 0, v187, vcc
	v_readlane_b32 s56, v252, 29
	v_readlane_b32 s57, v252, 30
	v_mul_f32_e32 v3, 0x3f317217, v1
	v_fma_f32 v3, v1, s41, -v3
	v_fmac_f32_e32 v3, 0x3377d1cf, v1
	v_fmac_f32_e32 v3, 0x3f317217, v1
	v_cmp_lt_f32_e64 vcc, |v1|, s68
	v_readlane_b32 s58, v252, 31
	v_readlane_b32 s59, v252, 32
	v_cndmask_b32_e32 v1, v1, v3, vcc
	v_sub_f32_e32 v1, v1, v2
	v_div_scale_f32 v2, s[14:15], s13, s13, v1
	v_rcp_f32_e32 v3, v2
	s_waitcnt vmcnt(3)
	v_div_scale_f32 v4, vcc, v1, s13, v1
	v_readlane_b32 s62, v252, 35
	v_fma_f32 v5, -v2, v3, 1.0
	v_fmac_f32_e32 v3, v5, v3
	v_mul_f32_e32 v5, v4, v3
	v_fma_f32 v6, -v2, v5, v4
	v_fmac_f32_e32 v5, v6, v3
	v_fma_f32 v2, -v2, v5, v4
	v_div_fmas_f32 v2, v2, v3, v5
	v_div_fixup_f32 v1, v2, s13, v1
	v_mul_f32_e32 v1, 0x41000000, v1
	v_cvt_i32_f32_e32 v1, v1
	v_cmp_lt_i32_e32 vcc, s0, v116
	v_readlane_b32 s63, v252, 36
	v_readlane_b32 s64, v252, 37
	v_min_i32_e32 v1, 7, v1
	v_cndmask_b32_e64 v2, 0, 16, vcc
	v_add_u32_e32 v1, 8, v1
	v_cmp_gt_i32_e32 vcc, 8, v0
	v_readlane_b32 s65, v252, 38
	v_readlane_b32 s66, v252, 39
	v_cndmask_b32_e32 v0, v1, v0, vcc
	v_add_u32_e32 v0, v0, v2
	v_lshl_or_b32 v0, v0, 3, s19
	v_ashrrev_i32_e32 v1, 31, v0
	v_lshl_add_u64 v[0:1], v[0:1], 2, s[60:61]
	global_load_dword v0, v[0:1], off
	v_lshl_add_u32 v1, v116, 2, 0
	v_add_u32_e32 v1, 0x1a800, v1
	v_readlane_b32 s67, v252, 40
	s_waitcnt vmcnt(0)
	v_mul_f32_e32 v0, 0x413504f3, v0
	ds_write_b32 v1, v0
.LBB0_251:
	s_or_b64 exec, exec, s[8:9]
	s_and_b32 s0, s10, 0x780
	s_sub_i32 s17, s3, s0
	s_lshl_b32 s0, s12, 3
	s_and_b32 s15, s0, 0xfffff800
	s_bfe_u32 s14, s12, 0x10004
	s_ashr_i32 s16, s15, 31
	s_mul_i32 s8, s15, 0xa080
	s_mul_hi_i32 s0, s15, 0xa080
	s_add_u32 s9, s4, s8
	s_addc_u32 s18, s5, s0
	s_lshl_b32 s13, s19, 8
	s_lshl_b32 s0, s19, 9
	s_lshl_b32 s8, s14, 8
	s_add_u32 s20, s9, s0
	s_addc_u32 s21, s18, 0
	s_add_u32 s22, s20, s8
	v_lshlrev_b32_e32 v0, 4, v116
	s_addc_u32 s23, s21, 0
	s_add_u32 s24, s22, 0x7000
	s_addc_u32 s25, s23, 0
	s_add_u32 s26, s20, 0x8000
	s_addc_u32 s27, s21, 0
	v_and_b32_e32 v26, 0xf0, v0
	v_mov_b32_e32 v27, v65
	v_lshl_add_u64 v[0:1], s[22:23], 0, v[26:27]
	s_mov_b64 s[22:23], 0x7000
	v_lshl_add_u64 v[154:155], v[0:1], 0, s[22:23]
	v_ashrrev_i32_e32 v161, 4, v116
	v_add_u32_e32 v27, 0x200, v116
	v_mad_i64_i32 v[0:1], s[22:23], v161, s69, v[154:155]
	v_ashrrev_i32_e32 v162, 4, v27
	v_mad_i64_i32 v[2:3], s[22:23], v162, s69, v[154:155]
	v_and_b32_e32 v246, 15, v190
	v_mul_u32_u24_e32 v247, 0xa080, v161
	v_lshl_add_u32 v246, v246, 4, v247
	v_add_u32_e32 v247, 0x141000, v246
	v_lshrrev_b32_e32 v239, 5, v190
	v_and_b32_e32 v169, 7, v239
	v_lshlrev_b32_e32 v169, 1, v169
	v_and_b32_e32 v172, 31, v190
	v_xor_b32_e32 v169, v169, v172
	v_mul_u32_u24_e32 v239, 0xa080, v239
	v_lshl_add_u32 v239, v169, 4, v239
	v_lshlrev_b32_e32 v169, 4, v190
	v_add_u32_e32 v169, 0x8800, v169
	v_lshrrev_b32_e32 v171, 2, v185
	v_and_b32_e32 v220, 3, v185
	v_lshlrev_b32_e32 v220, 3, v220
	v_lshl_add_u32 v220, v171, 9, v220
	v_add_u32_e32 v220, 0x8800, v220
	v_and_b32_e32 v171, 7, v171
	v_xor_b32_e32 v172, 0, v171
	v_lshl_add_u32 v172, v172, 5, v220
	v_xor_b32_e32 v175, 1, v171
	v_lshl_add_u32 v175, v175, 5, v220
	v_xor_b32_e32 v176, 2, v171
	v_lshl_add_u32 v176, v176, 5, v220
	v_xor_b32_e32 v181, 3, v171
	v_lshl_add_u32 v181, v181, 5, v220
	v_xor_b32_e32 v218, 4, v171
	v_lshl_add_u32 v218, v218, 5, v220
	v_xor_b32_e32 v219, 5, v171
	v_lshl_add_u32 v219, v219, 5, v220
	v_xor_b32_e32 v27, 7, v171
	v_xor_b32_e32 v171, 6, v171
	v_lshl_add_u32 v171, v171, 5, v220
	v_lshl_add_u32 v27, v27, 5, v220
	v_mov_b32_e32 v220, v171
	v_mov_b32_e32 v171, v27
	s_cmp_lg_u32 s32, 0
	s_cbranch_scc1 .Lch_skipB
	global_load_dwordx4 v[18:21], v[0:1], off
	global_load_dwordx4 v[22:25], v[2:3], off
	s_mov_b32 s29, 0x0
	s_add_u32 s72, s24, s29
	s_addc_u32 s73, s25, 0
	s_add_u32 s74, s26, s29
	s_addc_u32 s75, s27, 0
	s_add_u32 s76, s74, 0xa0800
	s_addc_u32 s77, s75, 0
	s_add_u32 s78, s76, 0xa0800
	s_addc_u32 s79, s77, 0
	s_add_u32 s80, s78, 0xa0800
	s_addc_u32 s81, s79, 0
	s_waitcnt vmcnt(2)
	global_load_dwordx4 v[206:209], v239, s[74:75]
	global_load_dwordx4 v[210:213], v239, s[76:77]
	global_load_dwordx4 v[214:217], v239, s[78:79]
	global_load_dwordx4 v[248:251], v239, s[80:81]
.Lch_skipB:
	s_lshl_b32 s18, s12, 7
	s_and_b32 s18, s18, 0x780
	s_add_i32 s18, s18, s2
	s_lshl_b32 s19, s19, 2
	v_readlane_b32 s52, v252, 25
	v_and_b32_e32 v165, 15, v116
	v_readlane_b32 s60, v252, 33
	v_readlane_b32 s61, v252, 34
	s_mov_b32 s9, s1
	v_bfe_u32 v43, v116, 4, 2
	v_lshlrev_b32_e32 v64, 4, v43
	v_add_u32_e32 v26, 0, v26
	v_lshlrev_b32_e32 v158, 3, v43
	v_mov_b32_e32 v0, s19
	s_add_i32 s19, s18, s15
	s_cmp_lg_u32 s32, 0
	s_cbranch_scc1 .Lch_q0
	global_load_dword v44, v0, s[60:61] offset:480
	global_load_dword v45, v0, s[60:61] offset:992
.Lch_q0:
	v_or_b32_e32 v2, s19, v165
	v_mov_b64_e32 v[0:1], s[4:5]
	v_mad_i64_i32 v[0:1], s[20:21], v2, s69, v[0:1]
	v_lshl_add_u64 v[0:1], v[0:1], 0, s[0:1]
	v_lshl_add_u64 v[0:1], v[0:1], 0, s[8:9]
	v_lshl_add_u64 v[0:1], v[0:1], 0, v[64:65]
	v_mov_b32_e32 v178, v0
	v_mov_b32_e32 v179, v1
	s_movk_i32 s0, 0x6000
	v_add_co_u32_e32 v8, vcc, s0, v0
	s_movk_i32 s0, 0x110
	s_mov_b64 s[8:9], 0x6000
	v_mul_lo_u32 v46, v161, s0
	v_lshl_add_u64 v[12:13], v[0:1], 0, s[8:9]
	v_addc_co_u32_e32 v9, vcc, 0, v1, vcc
	v_add_u32_e32 v166, v26, v46
	s_cmp_lg_u32 s32, 0
	s_cbranch_scc1 .Lch_q1
	global_load_dwordx4 v[0:3], v[12:13], off offset:64
	global_load_dwordx4 v[4:7], v[12:13], off offset:128
	s_nop 0
	global_load_dwordx4 v[8:11], v[8:9], off
	s_nop 0
	global_load_dwordx4 v[12:15], v[12:13], off offset:192
	s_waitcnt vmcnt(0)
.Lch_q1:
	s_cmp_lg_u32 s32, 0
	s_cbranch_scc1 .Lch_c1
	ds_write_b128 v166, v[18:21]
.Lch_c1:
	v_mul_lo_u32 v117, v162, s0
	v_add_u32_e32 v167, v26, v117
	s_waitcnt vmcnt(22)
	s_cmp_lg_u32 s32, 0
	s_cbranch_scc1 .Lch_c2
	ds_write_b128 v167, v[22:25]

.Lch_c3:
	v_readlane_b32 s8, v254, 60
	s_cmp_lg_u32 s32, 0
	s_cbranch_scc1 .Lch_q2
	s_waitcnt vmcnt(15)
	v_mul_f32_e32 v173, 0x413504f3, v44
	s_waitcnt vmcnt(14)
	v_mul_f32_e32 v174, 0x413504f3, v45
.Lch_q2:
	v_readlane_b32 s56, v252, 29
	v_readlane_b32 s57, v252, 30
	v_readlane_b32 s58, v252, 31
	v_readlane_b32 s59, v252, 32
	v_mad_u32_u24 v27, v165, s0, v64
	s_cselect_b32 s0, 0, 0
	s_cmp_lg_u32 s8, -1
	s_cselect_b32 s8, s8, 0
	v_mov_b32_e32 v64, v65
	v_lshlrev_b32_e32 v30, 2, v43
	v_add_u32_e32 v177, s0, v27
	s_add_i32 s8, s0, 0x4400
	s_add_i32 s0, s0, 0x11800
	v_mov_b64_e32 v[36:37], v[64:65]
	v_mov_b64_e32 v[44:45], v[64:65]
	v_mov_b64_e32 v[52:53], v[64:65]
	v_mov_b64_e32 v[60:61], v[64:65]
	v_mov_b64_e32 v[70:71], v[66:67]
	v_mov_b64_e32 v[78:79], v[66:67]
	v_mov_b64_e32 v[86:87], v[66:67]
	v_mov_b64_e32 v[94:95], v[66:67]
	v_mov_b64_e32 v[32:33], v[64:65]
	v_mov_b64_e32 v[40:41], v[64:65]
	v_mov_b64_e32 v[48:49], v[64:65]
	v_mov_b64_e32 v[56:57], v[64:65]
	v_mov_b64_e32 v[74:75], v[66:67]
	v_mov_b64_e32 v[82:83], v[66:67]
	v_mov_b64_e32 v[90:91], v[66:67]
	v_mov_b64_e32 v[98:99], v[66:67]
	s_mov_b32 s29, 0x504000
	s_add_u32 s72, s24, s29
	s_addc_u32 s73, s25, 0
	s_add_u32 s74, s26, s29
	s_addc_u32 s75, s27, 0
	s_add_u32 s76, s74, 0xa0800
	s_addc_u32 s77, s75, 0
	s_add_u32 s78, s76, 0xa0800
	s_addc_u32 s79, s77, 0
	s_add_u32 s80, s78, 0xa0800
	s_addc_u32 s81, s79, 0
	s_cmp_lg_u32 s32, 0
	s_cbranch_scc0 .Lch_nocopy
	s_waitcnt vmcnt(16)
	v_mov_b64_e32 v[0:1], v[100:101]
	v_mov_b64_e32 v[2:3], v[102:103]
	v_mov_b64_e32 v[4:5], v[104:105]
	v_mov_b64_e32 v[6:7], v[106:107]
	v_mov_b64_e32 v[8:9], v[108:109]
	v_mov_b64_e32 v[10:11], v[110:111]
	v_mov_b64_e32 v[12:13], v[112:113]
	v_mov_b64_e32 v[14:15], v[114:115]
.Lch_nocopy:
	s_mov_b32 s32, 1
	v_add_u32_e32 v191, s8, v27
	v_sub_u32_e32 v193, v30, v165
	s_mov_b32 s0, -2
	v_mov_b64_e32 v[38:39], v[66:67]
	v_mov_b64_e32 v[46:47], v[66:67]
	v_mov_b64_e32 v[54:55], v[66:67]
	v_mov_b64_e32 v[62:63], v[66:67]
	v_mov_b64_e32 v[68:69], v[64:65]
	v_mov_b64_e32 v[76:77], v[64:65]
	v_mov_b64_e32 v[84:85], v[64:65]
	v_mov_b64_e32 v[92:93], v[64:65]
	v_mov_b64_e32 v[34:35], v[66:67]
	v_mov_b64_e32 v[42:43], v[66:67]
	v_mov_b64_e32 v[50:51], v[66:67]
	v_mov_b64_e32 v[58:59], v[66:67]
	v_mov_b64_e32 v[72:73], v[64:65]
	v_mov_b64_e32 v[80:81], v[64:65]
	v_mov_b64_e32 v[88:89], v[64:65]
	v_mov_b64_e32 v[96:97], v[64:65]
	v_readlane_b32 s62, v252, 35
	v_readlane_b32 s63, v252, 36
	v_readlane_b32 s64, v252, 37
	v_readlane_b32 s65, v252, 38
	v_readlane_b32 s66, v252, 39
	v_readlane_b32 s67, v252, 40

.LBB0_262:
	s_waitcnt vmcnt(0)
	v_readlane_b32 s0, v255, 17
	s_cmpk_gt_i32 s0, 0x3ff
	s_cbranch_scc1 .LBB0_269
	s_add_u32 s4, s70, 0x31500000
	s_addc_u32 s5, s71, 0
	s_add_u32 s52, s70, 0x41900000
	s_addc_u32 s53, s71, 0
	s_add_u32 s54, s70, 0x9100000
	v_readlane_b32 s2, v255, 21
	s_addc_u32 s55, s71, 0
	v_readlane_b32 s3, v255, 22
	s_lshl_b32 s0, s2, 3
	s_lshl_b32 s2, s2, 11
	s_ashr_i32 s3, s2, 31
	v_readlane_b32 s8, v252, 9
	s_lshl_b64 s[2:3], s[2:3], 2
	v_readlane_b32 s14, v252, 15
	v_readlane_b32 s15, v252, 16
	s_add_u32 s56, s14, s2
	v_readlane_b32 s16, v252, 17
	s_addc_u32 s57, s15, s3
	v_readlane_b32 s17, v252, 18
	s_add_u32 s58, s16, s2
	v_readlane_b32 s2, v255, 19
	v_readlane_b32 s6, v255, 18
	v_readlane_b32 s10, v252, 11
	s_addc_u32 s59, s17, s3
	s_ashr_i32 s2, s2, 8
	s_lshl_b32 s3, s6, 5
	v_readlane_b32 s12, v252, 13
	s_and_b32 s10, s3, 0x60
	s_lshl_b32 s3, s2, 15
	v_readlane_b32 s11, v252, 12
	v_readlane_b32 s13, v252, 14
	v_readlane_b32 s18, v252, 19
	v_readlane_b32 s19, v252, 20
	v_readlane_b32 s20, v252, 21
	v_readlane_b32 s21, v252, 22
	v_readlane_b32 s22, v252, 23
	v_readlane_b32 s23, v252, 24
	s_add_i32 s12, s3, 0
	s_mul_i32 s3, s6, 0x4200
	v_readlane_b32 s24, v255, 17
	s_add_i32 s11, s12, 0x8800
	s_add_i32 s12, s12, 0xc800
	s_add_i32 s13, s3, 0
	s_lshl_b32 s14, s2, 7
	s_or_b32 s15, s10, 4
	s_or_b32 s16, s10, 8
	s_or_b32 s17, s10, 12
	s_or_b32 s18, s10, 16
	s_or_b32 s19, s10, 20
	s_or_b32 s20, s10, 24
	s_or_b32 s21, s10, 28
	s_lshl_b32 s22, s24, 4
	s_waitcnt lgkmcnt(0)
	s_lshl_b32 s23, s42, 4
	v_readlane_b32 s9, v252, 10
	s_branch .LBB0_265
